# P0 rmsnorm: sample-row groups moved from waves 0..127 (workgroups with conversion items) to waves 1920..2047
# speedup vs baseline: 1.0051x; 1.0051x over previous
.LBB0_45:
	v_readlane_b32 s8, v251, 0
	v_readlane_b32 s14, v251, 6
	v_readlane_b32 s15, v251, 7
	s_add_u32 s60, s14, 0x30d4000
	s_addc_u32 s61, s15, 0
	s_lshl_b32 s70, s57, 2
	v_mov_b32_e32 v82, v184
	s_cmpk_gt_i32 s57, 0x107f
	v_mbcnt_lo_u32_b32 v250, -1, 0
	v_readlane_b32 s9, v251, 1
	v_readlane_b32 s10, v251, 2
	v_readlane_b32 s11, v251, 3
	v_readlane_b32 s12, v251, 4
	v_readlane_b32 s13, v251, 5
	s_cbranch_scc1 .LBB0_50
	v_mbcnt_hi_u32_b32 v4, -1, v250
	v_and_b32_e32 v1, 64, v4
	v_add_u32_e32 v5, 64, v1
	v_xor_b32_e32 v1, 1, v4
	v_cmp_lt_i32_e32 vcc, v1, v5
	v_xor_b32_e32 v6, 2, v4
	v_readlane_b32 s12, v252, 0
	v_cndmask_b32_e32 v1, v4, v1, vcc
	v_cmp_lt_i32_e32 vcc, v6, v5
	s_lshl_b32 s8, s58, 5
	s_ashr_i32 s71, s70, 31
	v_cndmask_b32_e32 v6, v4, v6, vcc
	v_lshlrev_b32_e32 v92, 2, v6
	v_xor_b32_e32 v6, 4, v4
	v_cmp_lt_i32_e32 vcc, v6, v5
	v_readlane_b32 s16, v252, 4
	v_readlane_b32 s17, v252, 5
	v_cndmask_b32_e32 v6, v4, v6, vcc
	v_lshlrev_b32_e32 v93, 2, v6
	v_xor_b32_e32 v6, 8, v4
	v_cmp_lt_i32_e32 vcc, v6, v5
	v_readlane_b32 s18, v252, 6
	v_readlane_b32 s19, v252, 7
	v_cndmask_b32_e32 v6, v4, v6, vcc
	v_lshlrev_b32_e32 v94, 2, v6
	v_xor_b32_e32 v6, 16, v4
	v_cmp_lt_i32_e32 vcc, v6, v5
	v_readlane_b32 s20, v252, 8
	v_readlane_b32 s21, v252, 9
	v_readlane_b32 s22, v252, 10
	v_readlane_b32 s23, v252, 11
	v_cndmask_b32_e32 v6, v4, v6, vcc
	s_ashr_i32 s9, s8, 31
	s_lshl_b64 s[0:1], s[70:71], 12
	v_readlane_b32 s13, v252, 1
	v_lshlrev_b32_e32 v95, 2, v6
	v_xor_b32_e32 v6, 32, v4
	s_add_u32 s10, s12, s0
	v_readlane_b32 s16, v251, 0
	v_cmp_lt_i32_e32 vcc, v6, v5
	s_addc_u32 s11, s13, s1
	s_lshl_b64 s[12:13], s[8:9], 12
	s_lshl_b64 s[0:1], s[70:71], 11
	v_readlane_b32 s22, v251, 6
	v_readlane_b32 s24, v252, 12
	v_readlane_b32 s25, v252, 13
	v_cndmask_b32_e32 v4, v4, v6, vcc
	v_ashrrev_i32_e32 v83, 31, v82
	v_readlane_b32 s23, v251, 7
	s_add_u32 s0, s22, s0
	v_mov_b32_e32 v2, s24
	v_mov_b32_e32 v3, s25
	v_lshlrev_b32_e32 v96, 2, v4
	v_lshlrev_b64 v[4:5], 3, v[82:83]
	s_addc_u32 s1, s23, s1
	v_readlane_b32 s14, v252, 2
	v_readlane_b32 s15, v252, 3
	v_lshl_add_u64 v[86:87], v[82:83], 4, v[2:3]
	v_readlane_b32 s17, v251, 1
	v_readlane_b32 s20, v251, 4
	v_lshl_add_u64 v[2:3], s[0:1], 0, v[4:5]
	s_mov_b64 s[0:1], 0x30d5e00
	s_mov_b32 s7, 0
	v_lshlrev_b32_e32 v1, 2, v1
	v_lshl_add_u64 v[84:85], s[60:61], 0, v[4:5]
	v_lshl_add_u64 v[88:89], v[2:3], 0, s[0:1]
	s_lshl_b64 s[14:15], s[8:9], 11
	v_mov_b32_e32 v97, 0x358637bd
	s_mov_b32 s20, 0x800000
	s_mov_b64 s[16:17], s[70:71]
	v_readlane_b32 s26, v252, 14
	v_readlane_b32 s27, v252, 15
	v_readlane_b32 s18, v251, 2
	v_readlane_b32 s19, v251, 3
	v_readlane_b32 s21, v251, 5
	s_mov_b32 s98, 0
	s_lshr_b32 s99, s70, 2
	s_branch .LBB0_48
.LBB0_47:
	v_lshl_add_u64 v[22:23], v[82:83], 4, s[18:19]
	global_load_dwordx4 v[78:81], v[22:23], off
	global_load_dwordx4 v[74:77], v[22:23], off offset:1024
	global_load_dwordx4 v[62:65], v[22:23], off offset:3072
	global_load_dwordx4 v[70:73], v[22:23], off offset:2048
	s_mov_b64 s[18:19], 0x1000
	v_lshl_add_u64 v[2:3], v[22:23], 0, s[18:19]
	global_load_dwordx4 v[54:57], v[2:3], off offset:1024
	global_load_dwordx4 v[50:53], v[2:3], off offset:2048
	global_load_dwordx4 v[46:49], v[2:3], off offset:3072
	v_add_co_u32_e32 v2, vcc, 0x1000, v22
	s_lshl_b64 s[0:1], s[0:1], 11
	s_nop 0
	v_addc_co_u32_e32 v3, vcc, 0, v23, vcc
	global_load_dwordx4 v[66:69], v[2:3], off
	global_load_dwordx4 v[14:17], v[86:87], off
	global_load_dwordx4 v[10:13], v[86:87], off offset:1024
	global_load_dwordx4 v[6:9], v[86:87], off offset:2048
	s_nop 0
	global_load_dwordx4 v[2:5], v[86:87], off offset:3072
	s_mov_b64 s[18:19], 0x2000
	v_add_co_u32_e32 v32, vcc, 0x2000, v22
	v_lshl_add_u64 v[24:25], v[22:23], 0, s[18:19]
	s_mov_b64 s[18:19], 0x3000
	v_lshl_add_u64 v[90:91], v[84:85], 0, s[0:1]
	s_mov_b64 s[0:1], vcc
	v_add_co_u32_e32 v98, vcc, 0x3000, v22
	v_lshl_add_u64 v[30:31], v[22:23], 0, s[18:19]
	v_addc_co_u32_e64 v33, s[0:1], 0, v23, s[0:1]
	v_addc_co_u32_e32 v99, vcc, 0, v23, vcc
	global_load_dwordx4 v[42:45], v[24:25], off offset:1024
	global_load_dwordx4 v[34:37], v[24:25], off offset:2048
	global_load_dwordx4 v[26:29], v[30:31], off offset:1024
	global_load_dwordx4 v[18:21], v[30:31], off offset:2048
	global_load_dwordx4 v[38:41], v[24:25], off offset:3072
	global_load_dwordx4 v[58:61], v[32:33], off
	s_nop 0
	global_load_dwordx4 v[22:25], v[30:31], off offset:3072
	s_nop 0
	global_load_dwordx4 v[30:33], v[98:99], off
	s_movk_i32 s0, 0xf000
	s_add_u32 s16, s16, s8
	s_addc_u32 s17, s17, s9
	s_add_u32 s10, s10, s12
	s_addc_u32 s11, s11, s13
	s_add_i32 s98, s98, 1
	s_cmp_lg_u32 s98, 2
	s_cbranch_scc1 .Lp0_a
	s_movk_i32 s16, 0x7fff
	s_cmpk_lt_u32 s99, 0x780
	s_cbranch_scc1 .Lp0_a
	s_sub_i32 s100, 0x7ff, s99
	s_lshl_b32 s16, s100, 2
	s_add_i32 s16, s16, 0x4000
	s_sub_i32 s100, s100, s99
	s_lshl_b32 s100, s100, 13
	s_ashr_i32 s101, s100, 31
	s_add_u32 s14, s14, s100
	s_addc_u32 s15, s15, s101
.Lp0_a:
	s_cmpk_lt_i32 s16, 0x4200
	s_waitcnt vmcnt(19)
	v_pk_mul_f32 v[98:99], v[80:81], v[80:81]
	v_pk_mul_f32 v[100:101], v[78:79], v[78:79]
	s_waitcnt vmcnt(18)
	v_pk_mul_f32 v[102:103], v[76:77], v[76:77]
	v_pk_mul_f32 v[104:105], v[74:75], v[74:75]
	v_pk_mov_b32 v[110:111], v[100:101], v[98:99] op_sel:[1,0]
	v_mov_b32_e32 v101, v99
	v_pk_mov_b32 v[98:99], v[104:105], v[102:103] op_sel:[1,0]
	v_mov_b32_e32 v105, v103
	s_waitcnt vmcnt(16)
	v_mul_f32_e32 v106, v71, v71
	v_mul_f32_e32 v108, v73, v73
	v_pk_add_f32 v[100:101], v[110:111], v[100:101]
	v_pk_add_f32 v[98:99], v[98:99], v[104:105]
	v_mul_f32_e32 v114, v62, v62
	v_mul_f32_e32 v115, v63, v63
	v_mul_f32_e32 v116, v64, v64
	v_mul_f32_e32 v117, v65, v65
	v_pk_fma_f32 v[102:103], v[70:71], v[70:71], v[106:107] op_sel_hi:[1,1,0]
	v_pk_fma_f32 v[106:107], v[72:73], v[72:73], v[108:109] op_sel_hi:[1,1,0]
	v_pk_add_f32 v[100:101], v[100:101], v[100:101] op_sel:[0,1] op_sel_hi:[1,0]
	v_pk_add_f32 v[98:99], v[98:99], v[98:99] op_sel:[0,1] op_sel_hi:[1,0]
	v_mov_b32_e32 v103, v116
	v_mov_b32_e32 v107, v117
	v_mov_b32_e32 v101, v114
	v_mov_b32_e32 v99, v115
	v_pk_add_f32 v[102:103], v[102:103], v[106:107]
	v_pk_add_f32 v[98:99], v[100:101], v[98:99]
	s_waitcnt vmcnt(15)
	v_pk_mul_f32 v[108:109], v[56:57], v[56:57]
	v_pk_add_f32 v[98:99], v[98:99], v[102:103]
	v_pk_mul_f32 v[112:113], v[54:55], v[54:55]
	v_add_f32_e32 v99, v98, v99
	ds_bpermute_b32 v101, v1, v99
	v_pk_mov_b32 v[102:103], v[112:113], v[108:109] op_sel:[1,0]
	v_mov_b32_e32 v113, v109
	s_waitcnt vmcnt(12)
	v_pk_mul_f32 v[104:105], v[68:69], v[68:69]
	v_pk_mul_f32 v[106:107], v[66:67], v[66:67]
	s_waitcnt lgkmcnt(0)
	v_add_f32_e32 v99, v99, v101
	ds_bpermute_b32 v101, v92, v99
	v_pk_add_f32 v[102:103], v[102:103], v[112:113]
	v_mul_f32_e32 v98, v51, v51
	v_mul_f32_e32 v100, v53, v53
	v_mul_f32_e32 v114, v48, v48
	s_waitcnt lgkmcnt(0)
	v_add_f32_e32 v108, v99, v101
	ds_bpermute_b32 v109, v93, v108
	v_mul_f32_e32 v115, v49, v49
	v_pk_fma_f32 v[98:99], v[50:51], v[50:51], v[98:99] op_sel_hi:[1,1,0]
	v_pk_fma_f32 v[100:101], v[52:53], v[52:53], v[100:101] op_sel_hi:[1,1,0]
	v_mov_b32_e32 v99, v114
	s_waitcnt lgkmcnt(0)
	v_add_f32_e32 v116, v108, v109
	ds_bpermute_b32 v117, v94, v116
	v_pk_mov_b32 v[108:109], v[106:107], v[104:105] op_sel:[1,0]
	v_mov_b32_e32 v107, v105
	v_mov_b32_e32 v101, v115
	v_pk_add_f32 v[98:99], v[98:99], v[100:101]
	s_waitcnt lgkmcnt(0)
	v_add_f32_e32 v104, v116, v117
	ds_bpermute_b32 v112, v95, v104
	v_pk_add_f32 v[100:101], v[108:109], v[106:107]
	v_mul_f32_e32 v110, v46, v46
	v_mul_f32_e32 v111, v47, v47
	v_pk_add_f32 v[102:103], v[102:103], v[102:103] op_sel:[0,1] op_sel_hi:[1,0]
	s_waitcnt lgkmcnt(0)
	v_add_f32_e32 v104, v104, v112
	ds_bpermute_b32 v105, v96, v104
	v_pk_add_f32 v[100:101], v[100:101], v[100:101] op_sel:[0,1] op_sel_hi:[1,0]
	v_mov_b32_e32 v103, v111
	v_mov_b32_e32 v101, v110
	v_pk_add_f32 v[100:101], v[100:101], v[102:103]
	s_waitcnt lgkmcnt(0)
	v_add_f32_e32 v102, v104, v105
	v_fmamk_f32 v102, v102, 0x3a800000, v97
	v_mul_f32_e32 v103, 0x4b800000, v102
	v_cmp_gt_f32_e32 vcc, s20, v102
	v_pk_add_f32 v[98:99], v[100:101], v[98:99]
	s_nop 0
	v_cndmask_b32_e32 v102, v102, v103, vcc
	v_rsq_f32_e32 v102, v102
	v_add_f32_e32 v98, v98, v99
	ds_bpermute_b32 v99, v1, v98
	v_mul_f32_e32 v100, 0x45800000, v102
	v_cndmask_b32_e32 v100, v102, v100, vcc
	v_mul_f32_e32 v78, v78, v100
	v_mul_f32_e32 v79, v79, v100
	v_mul_f32_e32 v74, v74, v100
	v_mul_f32_e32 v80, v80, v100
	v_mul_f32_e32 v81, v81, v100
	v_mul_f32_e32 v75, v75, v100
	s_waitcnt vmcnt(11)
	v_mul_f32_e32 v78, v14, v78
	v_mul_f32_e32 v79, v15, v79
	s_waitcnt vmcnt(10)
	v_mul_f32_e32 v101, v10, v74
	v_cvt_pk_bf16_f32 v74, v78, v79
	v_mul_f32_e32 v80, v16, v80
	v_mul_f32_e32 v81, v17, v81
	v_mul_f32_e32 v102, v11, v75
	v_cvt_pk_bf16_f32 v75, v80, v81
	global_store_dwordx2 v[90:91], v[74:75], off
	s_waitcnt lgkmcnt(0)
	v_add_f32_e32 v74, v98, v99
	ds_bpermute_b32 v75, v92, v74
	v_mul_f32_e32 v70, v70, v100
	v_mul_f32_e32 v71, v71, v100
	s_waitcnt vmcnt(10)
	v_mul_f32_e32 v70, v6, v70
	v_mul_f32_e32 v71, v7, v71
	s_waitcnt lgkmcnt(0)
	v_add_f32_e32 v74, v74, v75
	ds_bpermute_b32 v75, v93, v74
	v_cvt_pk_bf16_f32 v70, v70, v71
	v_mul_f32_e32 v71, v72, v100
	v_mul_f32_e32 v71, v8, v71
	v_mul_f32_e32 v73, v73, v100
	s_waitcnt lgkmcnt(0)
	v_add_f32_e32 v72, v74, v75
	ds_bpermute_b32 v74, v94, v72
	v_mul_f32_e32 v73, v9, v73
	v_cvt_pk_bf16_f32 v71, v71, v73
	global_store_dwordx2 v[90:91], v[70:71], off offset:1024
	v_mul_f32_e32 v62, v62, v100
	s_waitcnt lgkmcnt(0)
	v_add_f32_e32 v70, v72, v74
	ds_bpermute_b32 v71, v95, v70
	v_mul_f32_e32 v63, v63, v100
	s_waitcnt vmcnt(10)
	v_mul_f32_e32 v62, v2, v62
	v_mul_f32_e32 v63, v3, v63
	v_cvt_pk_bf16_f32 v62, v62, v63
	s_waitcnt lgkmcnt(0)
	v_add_f32_e32 v70, v70, v71
	ds_bpermute_b32 v71, v96, v70
	v_mul_f32_e32 v63, v64, v100
	v_mul_f32_e32 v64, v65, v100
	v_mul_f32_e32 v63, v4, v63
	v_mul_f32_e32 v64, v5, v64
	s_waitcnt lgkmcnt(0)
	v_add_f32_e32 v65, v70, v71
	v_fmamk_f32 v65, v65, 0x3a800000, v97
	v_mul_f32_e32 v70, 0x4b800000, v65
	v_cmp_gt_f32_e32 vcc, s20, v65
	v_cvt_pk_bf16_f32 v63, v63, v64
	global_store_dwordx2 v[90:91], v[62:63], off offset:1536
	v_mul_f32_e32 v77, v77, v100
	v_cndmask_b32_e32 v65, v65, v70, vcc
	v_rsq_f32_e32 v65, v65
	v_mul_f32_e32 v76, v76, v100
	v_mul_f32_e32 v77, v13, v77
	v_mul_f32_e32 v103, v12, v76
	v_mul_f32_e32 v62, 0x45800000, v65
	v_cndmask_b32_e32 v72, v65, v62, vcc
	v_mul_f32_e32 v62, v66, v72
	v_mul_f32_e32 v63, v67, v72
	v_mul_f32_e32 v62, v14, v62
	v_mul_f32_e32 v63, v15, v63
	v_cvt_pk_bf16_f32 v62, v62, v63
	v_mul_f32_e32 v63, v68, v72
	v_mul_f32_e32 v64, v69, v72
	v_mul_f32_e32 v63, v16, v63
	v_mul_f32_e32 v64, v17, v64
	v_cvt_pk_bf16_f32 v63, v63, v64
	v_add_co_u32_e32 v64, vcc, s0, v88
	v_cvt_pk_bf16_f32 v76, v101, v102
	v_cvt_pk_bf16_f32 v77, v103, v77
	global_store_dwordx2 v[90:91], v[76:77], off offset:512
	s_nop 0
	v_addc_co_u32_e32 v65, vcc, -1, v89, vcc
	global_store_dwordx2 v[64:65], v[62:63], off offset:-1536
	s_waitcnt vmcnt(7)
	v_pk_mul_f32 v[62:63], v[60:61], v[60:61]
	v_pk_mul_f32 v[66:67], v[58:59], v[58:59]
	v_mul_f32_e32 v54, v54, v72
	v_pk_mov_b32 v[68:69], v[66:67], v[62:63] op_sel:[1,0]
	v_mov_b32_e32 v67, v63
	v_pk_add_f32 v[62:63], v[68:69], v[66:67]
	v_pk_mul_f32 v[66:67], v[44:45], v[44:45]
	v_pk_mul_f32 v[68:69], v[42:43], v[42:43]
	v_mul_f32_e32 v55, v55, v72
	v_pk_mov_b32 v[70:71], v[68:69], v[66:67] op_sel:[1,0]
	v_mov_b32_e32 v69, v67
	v_mul_f32_e32 v54, v10, v54
	v_mul_f32_e32 v55, v11, v55
	v_pk_add_f32 v[66:67], v[70:71], v[68:69]
	v_cvt_pk_bf16_f32 v54, v54, v55
	v_mul_f32_e32 v55, v56, v72
	v_mul_f32_e32 v56, v38, v38
	v_mul_f32_e32 v68, v39, v39
	v_pk_add_f32 v[62:63], v[62:63], v[62:63] op_sel:[0,1] op_sel_hi:[1,0]
	v_pk_add_f32 v[66:67], v[66:67], v[66:67] op_sel:[0,1] op_sel_hi:[1,0]
	v_mov_b32_e32 v63, v56
	v_mov_b32_e32 v67, v68
	v_mul_f32_e32 v56, v35, v35
	v_mul_f32_e32 v69, v40, v40
	v_pk_add_f32 v[62:63], v[62:63], v[66:67]
	v_pk_fma_f32 v[66:67], v[34:35], v[34:35], v[56:57] op_sel_hi:[1,1,0]
	v_mul_f32_e32 v56, v37, v37
	v_mul_f32_e32 v70, v41, v41
	v_mov_b32_e32 v67, v69
	v_pk_fma_f32 v[68:69], v[36:37], v[36:37], v[56:57] op_sel_hi:[1,1,0]
	v_mul_f32_e32 v57, v57, v72
	v_mov_b32_e32 v69, v70
	v_pk_add_f32 v[66:67], v[66:67], v[68:69]
	v_mul_f32_e32 v55, v12, v55
	v_pk_add_f32 v[62:63], v[62:63], v[66:67]
	v_mul_f32_e32 v57, v13, v57
	v_add_f32_e32 v56, v62, v63
	ds_bpermute_b32 v62, v1, v56
	v_cvt_pk_bf16_f32 v55, v55, v57
	global_store_dwordx2 v[64:65], v[54:55], off offset:-1024
	v_mul_f32_e32 v50, v50, v72
	v_mul_f32_e32 v51, v51, v72
	s_waitcnt lgkmcnt(0)
	v_add_f32_e32 v56, v56, v62
	ds_bpermute_b32 v57, v92, v56
	v_mul_f32_e32 v50, v6, v50
	v_mul_f32_e32 v51, v7, v51
	v_cvt_pk_bf16_f32 v50, v50, v51
	v_mul_f32_e32 v51, v52, v72
	s_waitcnt lgkmcnt(0)
	v_add_f32_e32 v54, v56, v57
	ds_bpermute_b32 v55, v93, v54
	v_mul_f32_e32 v51, v8, v51
	v_mul_f32_e32 v53, v53, v72
	v_mul_f32_e32 v53, v9, v53
	v_cvt_pk_bf16_f32 v51, v51, v53
	s_waitcnt lgkmcnt(0)
	v_add_f32_e32 v52, v54, v55
	ds_bpermute_b32 v54, v94, v52
	global_store_dwordx2 v[64:65], v[50:51], off offset:-512
	v_mul_f32_e32 v46, v46, v72
	v_mul_f32_e32 v47, v47, v72
	v_mul_f32_e32 v46, v2, v46
	s_waitcnt lgkmcnt(0)
	v_add_f32_e32 v50, v52, v54
	ds_bpermute_b32 v51, v95, v50
	v_mul_f32_e32 v47, v3, v47
	v_cvt_pk_bf16_f32 v46, v46, v47
	v_mul_f32_e32 v47, v48, v72
	v_mul_f32_e32 v48, v49, v72
	s_waitcnt lgkmcnt(0)
	v_add_f32_e32 v50, v50, v51
	ds_bpermute_b32 v51, v96, v50
	v_mul_f32_e32 v47, v4, v47
	v_mul_f32_e32 v48, v5, v48
	v_cvt_pk_bf16_f32 v47, v47, v48
	global_store_dwordx2 v[88:89], v[46:47], off offset:-4096
	s_waitcnt lgkmcnt(0)
	v_add_f32_e32 v49, v50, v51
	v_fmamk_f32 v49, v49, 0x3a800000, v97
	v_mul_f32_e32 v50, 0x4b800000, v49
	v_cmp_gt_f32_e32 vcc, s20, v49
	s_nop 1
	v_cndmask_b32_e32 v49, v49, v50, vcc
	v_rsq_f32_e32 v49, v49
	s_nop 0
	v_mul_f32_e32 v46, 0x45800000, v49
	v_cndmask_b32_e32 v54, v49, v46, vcc
	v_mul_f32_e32 v46, v58, v54
	v_mul_f32_e32 v47, v59, v54
	v_mul_f32_e32 v46, v14, v46
	v_mul_f32_e32 v47, v15, v47
	v_cvt_pk_bf16_f32 v46, v46, v47
	v_mul_f32_e32 v47, v60, v54
	v_mul_f32_e32 v47, v16, v47
	v_mul_f32_e32 v48, v61, v54
	v_mul_f32_e32 v48, v17, v48
	v_cvt_pk_bf16_f32 v47, v47, v48
	global_store_dwordx2 v[88:89], v[46:47], off offset:-3584
	s_waitcnt vmcnt(9)
	v_pk_mul_f32 v[46:47], v[32:33], v[32:33]
	v_pk_mul_f32 v[48:49], v[30:31], v[30:31]
	v_mul_f32_e32 v42, v42, v54
	v_pk_mov_b32 v[50:51], v[48:49], v[46:47] op_sel:[1,0]
	v_mov_b32_e32 v49, v47
	v_pk_add_f32 v[46:47], v[50:51], v[48:49]
	v_pk_mul_f32 v[48:49], v[28:29], v[28:29]
	v_pk_mul_f32 v[50:51], v[26:27], v[26:27]
	v_mul_f32_e32 v43, v43, v54
	v_pk_mov_b32 v[52:53], v[50:51], v[48:49] op_sel:[1,0]
	v_mov_b32_e32 v51, v49
	v_mul_f32_e32 v42, v10, v42
	v_mul_f32_e32 v43, v11, v43
	v_pk_add_f32 v[48:49], v[52:53], v[50:51]
	v_cvt_pk_bf16_f32 v42, v42, v43
	v_mul_f32_e32 v43, v44, v54
	v_mul_f32_e32 v44, v22, v22
	v_mul_f32_e32 v50, v23, v23
	v_pk_add_f32 v[46:47], v[46:47], v[46:47] op_sel:[0,1] op_sel_hi:[1,0]
	v_pk_add_f32 v[48:49], v[48:49], v[48:49] op_sel:[0,1] op_sel_hi:[1,0]
	v_mov_b32_e32 v47, v44
	v_mov_b32_e32 v49, v50
	v_mul_f32_e32 v44, v19, v19
	v_mul_f32_e32 v51, v24, v24
	v_pk_add_f32 v[46:47], v[46:47], v[48:49]
	v_pk_fma_f32 v[48:49], v[18:19], v[18:19], v[44:45] op_sel_hi:[1,1,0]
	v_mul_f32_e32 v44, v21, v21
	v_mul_f32_e32 v52, v25, v25
	v_mov_b32_e32 v49, v51
	v_pk_fma_f32 v[50:51], v[20:21], v[20:21], v[44:45] op_sel_hi:[1,1,0]
	v_mul_f32_e32 v45, v45, v54
	v_mov_b32_e32 v51, v52
	v_pk_add_f32 v[48:49], v[48:49], v[50:51]
	v_mul_f32_e32 v43, v12, v43
	v_pk_add_f32 v[46:47], v[46:47], v[48:49]
	v_mul_f32_e32 v45, v13, v45
	v_add_f32_e32 v44, v46, v47
	ds_bpermute_b32 v46, v1, v44
	v_cvt_pk_bf16_f32 v43, v43, v45
	global_store_dwordx2 v[88:89], v[42:43], off offset:-3072
	v_mul_f32_e32 v34, v34, v54
	v_mul_f32_e32 v35, v35, v54
	s_waitcnt lgkmcnt(0)
	v_add_f32_e32 v44, v44, v46
	ds_bpermute_b32 v45, v92, v44
	v_mul_f32_e32 v34, v6, v34
	v_mul_f32_e32 v35, v7, v35
	v_cvt_pk_bf16_f32 v34, v34, v35
	v_mul_f32_e32 v35, v36, v54
	s_waitcnt lgkmcnt(0)
	v_add_f32_e32 v42, v44, v45
	ds_bpermute_b32 v43, v93, v42
	v_mul_f32_e32 v35, v8, v35
	v_mul_f32_e32 v37, v37, v54
	v_mul_f32_e32 v37, v9, v37
	v_cvt_pk_bf16_f32 v35, v35, v37
	s_waitcnt lgkmcnt(0)
	v_add_f32_e32 v36, v42, v43
	ds_bpermute_b32 v42, v94, v36
	global_store_dwordx2 v[88:89], v[34:35], off offset:-2560
	v_mul_f32_e32 v37, v39, v54
	v_mul_f32_e32 v37, v3, v37
	s_waitcnt lgkmcnt(0)
	v_add_f32_e32 v34, v36, v42
	ds_bpermute_b32 v35, v95, v34
	v_mul_f32_e32 v36, v38, v54
	v_mul_f32_e32 v36, v2, v36
	s_waitcnt lgkmcnt(0)
	v_add_f32_e32 v35, v34, v35
	ds_bpermute_b32 v38, v96, v35
	v_cvt_pk_bf16_f32 v34, v36, v37
	v_mul_f32_e32 v37, v41, v54
	v_mul_f32_e32 v36, v40, v54
	v_mul_f32_e32 v36, v4, v36
	s_waitcnt lgkmcnt(0)
	v_add_f32_e32 v35, v35, v38
	v_fmamk_f32 v35, v35, 0x3a800000, v97
	v_mul_f32_e32 v38, 0x4b800000, v35
	v_cmp_gt_f32_e32 vcc, s20, v35
	s_nop 1
	v_cndmask_b32_e32 v35, v35, v38, vcc
	v_rsq_f32_e32 v38, v35
	v_mul_f32_e32 v35, v5, v37
	v_cvt_pk_bf16_f32 v35, v36, v35
	global_store_dwordx2 v[88:89], v[34:35], off offset:-2048
	v_mul_f32_e32 v34, 0x45800000, v38
	v_cndmask_b32_e32 v34, v38, v34, vcc
	v_mul_f32_e32 v30, v30, v34
	v_mul_f32_e32 v14, v14, v30
	v_mul_f32_e32 v30, v31, v34
	v_mul_f32_e32 v15, v15, v30
	v_cvt_pk_bf16_f32 v14, v14, v15
	v_mul_f32_e32 v15, v32, v34
	v_mul_f32_e32 v15, v16, v15
	v_mul_f32_e32 v16, v33, v34
	v_mul_f32_e32 v16, v17, v16
	v_cvt_pk_bf16_f32 v15, v15, v16
	global_store_dwordx2 v[88:89], v[14:15], off offset:-1536
	v_mul_f32_e32 v14, v26, v34
	v_mul_f32_e32 v10, v10, v14
	v_mul_f32_e32 v14, v27, v34
	v_mul_f32_e32 v11, v11, v14
	v_cvt_pk_bf16_f32 v10, v10, v11
	v_mul_f32_e32 v11, v28, v34
	v_mul_f32_e32 v11, v12, v11
	v_mul_f32_e32 v12, v29, v34
	v_mul_f32_e32 v12, v13, v12
	v_cvt_pk_bf16_f32 v11, v11, v12
	global_store_dwordx2 v[88:89], v[10:11], off offset:-1024
	v_mul_f32_e32 v10, v18, v34
	v_mul_f32_e32 v6, v6, v10
	v_mul_f32_e32 v10, v19, v34
	v_mul_f32_e32 v7, v7, v10
	v_cvt_pk_bf16_f32 v6, v6, v7
	v_mul_f32_e32 v7, v20, v34
	v_mul_f32_e32 v7, v8, v7
	v_mul_f32_e32 v8, v21, v34
	v_mul_f32_e32 v8, v9, v8
	v_cvt_pk_bf16_f32 v7, v7, v8
	global_store_dwordx2 v[88:89], v[6:7], off offset:-512
	v_mul_f32_e32 v6, v22, v34
	v_mul_f32_e32 v2, v2, v6
	v_mul_f32_e32 v6, v23, v34
	v_mul_f32_e32 v3, v3, v6
	v_cvt_pk_bf16_f32 v2, v2, v3
	v_mul_f32_e32 v3, v24, v34
	v_mul_f32_e32 v3, v4, v3
	v_mul_f32_e32 v4, v25, v34
	v_mul_f32_e32 v4, v5, v4
	v_cvt_pk_bf16_f32 v3, v3, v4
	global_store_dwordx2 v[88:89], v[2:3], off
	v_lshl_add_u64 v[88:89], v[88:89], 0, s[14:15]
	s_cbranch_scc0 .LBB0_50
